# slot pass takes both layers of FFN up/down weights (whole layer loop), prologue keeps only the tensors needed by the first phases
# baseline (speedup 1.0000x reference)
; template <class F> DI void tr_items(const F& f, int Kdst, int Nrows, bf16_t* WT, LAS float* scr, int gw, int NGW, int lane, int& cum) {
;     const int nblk = Nrows / 32, nitems = (Kdst / 64) * nblk;
;     int first = (gw - cum) % NGW; if (first < 0) first += NGW; cum = (cum + nitems) % NGW;
;     for (int item = first; item < nitems; item += NGW) {
; DI void phase_prologue(int wv, const ArgP a, LAS unsigned char* lds, int parts) {
;     ...
;         { FWUP f{a.in(23) + (size_t)l * 1024 * 5632, a.in(22) + l * 1024}; tr_items(f, 1024, 5632, (bf16_t*)(ws + (l ? O_WUPT1 : O_WUPT0)), scr, gw, NGW, lane, cum); }
.LBB0_294:
	v_subrev_u32_e32 v4, s42, v0
	v_sub_u32_e32 v6, 0, v4
	v_ashrrev_i32_e32 v5, 31, v4
	v_max_i32_e32 v4, v4, v6
	v_mul_hi_u32 v6, v4, s25
	v_mul_lo_u32 v6, v6, s15
	v_sub_u32_e32 v4, v4, v6
	v_subrev_u32_e32 v6, s15, v4
	v_cmp_le_u32_e32 vcc, s15, v4
	s_nop 1
	v_cndmask_b32_e32 v4, v4, v6, vcc
	v_subrev_u32_e32 v6, s15, v4
	v_cmp_le_u32_e32 vcc, s15, v4
	s_nop 1
	v_cndmask_b32_e32 v4, v4, v6, vcc
	v_xor_b32_e32 v4, v4, v5
	v_sub_u32_e32 v4, v4, v5
	v_ashrrev_i32_e32 v5, 31, v4
	v_and_b32_e32 v5, s14, v5
	v_add_u32_e32 v7, v5, v4
	v_cmp_gt_i32_e32 vcc, s27, v7
	s_and_b64 vcc, vcc, s[96:97]
	s_and_saveexec_b64 s[16:17], vcc
	s_cbranch_execz .LBB0_297
	s_mul_i32 s0, s43, 0x1600000
	s_waitcnt lgkmcnt(0)
	s_add_u32 s18, s10, s0
	s_addc_u32 s19, s11, 0
	s_lshl_b32 s0, s43, 10
	s_lshl_b64 s[4:5], s[0:1], 2
	s_add_u32 s20, s8, s4
	s_addc_u32 s21, s9, s5
	s_and_b64 s[4:5], s[6:7], exec
	s_cselect_b32 s0, 0x44eb000, 0
	v_lshl_add_u64 v[4:5], v[2:3], 0, s[0:1]
	v_lshlrev_b32_e32 v6, 5, v7
	v_lshlrev_b32_e32 v8, 4, v7
	s_mov_b64 s[22:23], 0
